# v66 + attention PV: 25 f32->bf16 RNE bit-trick packs (bfe/add3 x2, lshr, and_or) replaced by v_cvt_pk_bf16_f32 (same rounding, baseline uses both forms)
# speedup vs baseline: 1.0048x; 1.0016x over previous
; #define EXP2(x) __builtin_amdgcn_exp2f(x)
; #define SHFL_XOR3(v, m, lane) shfl_from((v), (lane) ^ (m))
; DEV void attn_compute(const AttnU& a, const bf16x8 (&qf)[4], int tq, bf16_t* OG, float* LSE, LAS unsigned char* lds, int tid) {
;     ...
;     mx = fmaxf(mx, SHFL_XOR3(mx, 32, lane));
;     float rs = 0.f;
; #pragma unroll
;     for (int sb = 0; sb < 5; ++sb)
; #pragma unroll
;         for (int rg = 0; rg < 16; ++rg) { const float p = EXP2(s[sb][rg] - mx); s[sb][rg] = p; rs += p; }
.LBB0_821:
	s_mov_b32 s29, 0xf149f2ca
	v_max3_f32 v3, v49, s29, v48
	v_max3_f32 v3, v3, v51, v50
	v_max3_f32 v3, v3, v70, v52
	v_max3_f32 v3, v3, v73, v72
	v_max3_f32 v3, v3, v75, v74
	v_max3_f32 v3, v3, v77, v76
	v_max3_f32 v3, v3, v80, v79
	v_max3_f32 v3, v3, v82, v81
	v_max3_f32 v3, v3, v84, v83
	v_max3_f32 v3, v3, v86, v85
	v_max3_f32 v3, v3, v88, v87
	v_max3_f32 v3, v3, v90, v89
	v_max3_f32 v3, v3, v92, v91
	v_max3_f32 v3, v3, v94, v93
	v_max3_f32 v3, v3, v96, v95
	v_max3_f32 v3, v3, v98, v97
	v_max3_f32 v3, v3, v100, v99
	v_max3_f32 v3, v3, v102, v101
	v_max3_f32 v3, v3, v104, v103
	v_max3_f32 v3, v3, v106, v105
	v_max3_f32 v3, v3, v108, v107
	v_max3_f32 v3, v3, v153, v109
	v_max3_f32 v3, v3, v155, v154
	v_max3_f32 v3, v3, v157, v156
	v_max3_f32 v3, v3, v159, v158
	v_max3_f32 v3, v3, v161, v160
	v_max3_f32 v3, v3, v163, v162
	v_max3_f32 v3, v3, v165, v164
	v_max3_f32 v3, v3, v187, v166
	v_max3_f32 v3, v3, v193, v192
	v_max3_f32 v3, v3, v196, v195
	v_max3_f32 v3, v3, v204, v201
	v_max3_f32 v3, v3, v54, v46
	v_max3_f32 v3, v3, v1, v0
	v_max3_f32 v3, v3, v56, v55
	v_max3_f32 v3, v3, v5, v4
	v_max3_f32 v3, v3, v7, v6
	v_and_b32_e32 v2, 63, v146
	v_max3_f32 v3, v3, v9, v8
	v_max3_f32 v3, v3, v11, v10
	v_lshlrev_b32_e32 v12, 2, v2
	v_max3_f32 v3, v3, v58, v57
	v_xor_b32_e32 v53, 0x80, v12
	ds_bpermute_b32 v12, v53, v3
	v_mov_b32_e32 v78, 0
	v_mov_b32_e32 v59, 0
	v_mov_b32_e32 v60, 0
	v_mov_b32_e32 v61, 0
	s_waitcnt lgkmcnt(0)
	v_max_f32_e32 v12, v12, v12
	v_max_f32_e32 v3, v3, v12
	v_sub_f32_e32 v12, v49, v3
	v_exp_f32_e32 v223, v12
	v_sub_f32_e32 v12, v48, v3
	v_exp_f32_e32 v225, v12
	v_sub_f32_e32 v12, v51, v3
	v_exp_f32_e32 v224, v12
	v_sub_f32_e32 v12, v50, v3
	v_exp_f32_e32 v227, v12
	v_sub_f32_e32 v13, v70, v3
	v_add_f32_e32 v12, 0, v223
	v_exp_f32_e32 v226, v13
	v_sub_f32_e32 v13, v52, v3
	v_add_f32_e32 v12, v225, v12
	v_exp_f32_e32 v229, v13
	v_sub_f32_e32 v13, v73, v3
	v_add_f32_e32 v12, v224, v12
	v_exp_f32_e32 v228, v13
	v_sub_f32_e32 v13, v72, v3
	v_add_f32_e32 v12, v227, v12
	v_exp_f32_e32 v230, v13
	v_sub_f32_e32 v13, v75, v3
	v_add_f32_e32 v12, v226, v12
	v_exp_f32_e32 v215, v13
	v_sub_f32_e32 v13, v74, v3
	v_add_f32_e32 v12, v229, v12
	v_exp_f32_e32 v217, v13
	v_sub_f32_e32 v13, v77, v3
	v_add_f32_e32 v12, v228, v12
	v_exp_f32_e32 v216, v13
	v_sub_f32_e32 v13, v76, v3
	v_add_f32_e32 v12, v230, v12
	v_exp_f32_e32 v219, v13
	v_sub_f32_e32 v13, v80, v3
	v_add_f32_e32 v12, v215, v12
	v_exp_f32_e32 v218, v13
	v_sub_f32_e32 v13, v79, v3
	v_add_f32_e32 v12, v217, v12
	v_exp_f32_e32 v221, v13
	v_sub_f32_e32 v13, v82, v3
	v_add_f32_e32 v12, v216, v12
	v_exp_f32_e32 v220, v13
	v_sub_f32_e32 v13, v81, v3
	v_add_f32_e32 v12, v219, v12
	v_exp_f32_e32 v222, v13
	v_sub_f32_e32 v13, v84, v3
	v_add_f32_e32 v12, v218, v12
	v_exp_f32_e32 v208, v13
	v_sub_f32_e32 v13, v83, v3
	v_add_f32_e32 v12, v221, v12
	v_exp_f32_e32 v207, v13
	v_sub_f32_e32 v13, v86, v3
	v_add_f32_e32 v12, v220, v12
	v_exp_f32_e32 v209, v13
	v_sub_f32_e32 v13, v85, v3
	v_add_f32_e32 v12, v222, v12
	v_exp_f32_e32 v211, v13
	v_sub_f32_e32 v13, v88, v3
	v_add_f32_e32 v12, v208, v12
	v_exp_f32_e32 v210, v13
	v_sub_f32_e32 v13, v87, v3
	v_add_f32_e32 v12, v207, v12
	v_exp_f32_e32 v213, v13
	v_sub_f32_e32 v13, v90, v3
	v_add_f32_e32 v12, v209, v12
	v_exp_f32_e32 v212, v13
	v_sub_f32_e32 v13, v89, v3
	v_add_f32_e32 v12, v211, v12
	v_exp_f32_e32 v214, v13
	v_sub_f32_e32 v13, v92, v3
	v_add_f32_e32 v12, v210, v12
	v_exp_f32_e32 v194, v13
	v_sub_f32_e32 v13, v91, v3
	v_add_f32_e32 v12, v213, v12
	v_exp_f32_e32 v198, v13
	v_sub_f32_e32 v13, v94, v3
	v_add_f32_e32 v12, v212, v12
	v_exp_f32_e32 v197, v13
	v_sub_f32_e32 v13, v93, v3
	v_add_f32_e32 v12, v214, v12
	v_exp_f32_e32 v200, v13
	v_sub_f32_e32 v13, v96, v3
	v_add_f32_e32 v12, v194, v12
	v_exp_f32_e32 v199, v13
	v_sub_f32_e32 v13, v95, v3
	v_add_f32_e32 v12, v198, v12
	v_exp_f32_e32 v203, v13
	v_sub_f32_e32 v13, v98, v3
	v_add_f32_e32 v12, v197, v12
	v_exp_f32_e32 v202, v13
	v_sub_f32_e32 v13, v97, v3
	v_add_f32_e32 v12, v200, v12
	v_exp_f32_e32 v205, v13
	v_sub_f32_e32 v13, v100, v3
	v_add_f32_e32 v12, v199, v12
	v_exp_f32_e32 v183, v13
	v_sub_f32_e32 v13, v99, v3
	v_add_f32_e32 v12, v203, v12
	v_exp_f32_e32 v185, v13
	v_sub_f32_e32 v13, v102, v3
	v_add_f32_e32 v12, v202, v12
	v_exp_f32_e32 v184, v13
	v_sub_f32_e32 v13, v101, v3
	v_add_f32_e32 v12, v205, v12
	v_exp_f32_e32 v188, v13
	v_sub_f32_e32 v13, v104, v3
	v_add_f32_e32 v12, v183, v12
	v_exp_f32_e32 v186, v13
	v_sub_f32_e32 v13, v103, v3
	v_add_f32_e32 v12, v185, v12
	v_exp_f32_e32 v190, v13
	v_sub_f32_e32 v13, v106, v3
	v_add_f32_e32 v12, v184, v12
	v_exp_f32_e32 v189, v13
	v_sub_f32_e32 v13, v105, v3
	v_add_f32_e32 v12, v188, v12
	v_exp_f32_e32 v191, v13
	v_sub_f32_e32 v13, v108, v3
	v_add_f32_e32 v12, v186, v12
	v_exp_f32_e32 v175, v13
	v_sub_f32_e32 v13, v107, v3
	v_add_f32_e32 v12, v190, v12
	v_exp_f32_e32 v177, v13
	v_sub_f32_e32 v13, v153, v3
	v_add_f32_e32 v12, v189, v12
	v_exp_f32_e32 v176, v13
	v_sub_f32_e32 v13, v109, v3
	v_add_f32_e32 v12, v191, v12
	v_exp_f32_e32 v179, v13
	v_sub_f32_e32 v13, v155, v3
	v_add_f32_e32 v12, v175, v12
	v_exp_f32_e32 v178, v13
	v_sub_f32_e32 v13, v154, v3
	v_add_f32_e32 v12, v177, v12
	v_exp_f32_e32 v181, v13
	v_sub_f32_e32 v13, v157, v3
	v_add_f32_e32 v12, v176, v12
	v_exp_f32_e32 v180, v13
	v_sub_f32_e32 v13, v156, v3
	v_add_f32_e32 v12, v179, v12
	v_exp_f32_e32 v182, v13
	v_sub_f32_e32 v13, v159, v3
	v_add_f32_e32 v12, v178, v12
	v_exp_f32_e32 v167, v13
	v_sub_f32_e32 v13, v158, v3
	v_add_f32_e32 v12, v181, v12
	v_exp_f32_e32 v169, v13
	v_sub_f32_e32 v13, v161, v3
	v_add_f32_e32 v12, v180, v12
	v_exp_f32_e32 v168, v13
; #define LAS __attribute__((address_space(3)))
; #define EXP2(x) __builtin_amdgcn_exp2f(x)
; #define SHFL_XOR3(v, m, lane) shfl_from((v), (lane) ^ (m))
; #define MFMA32(a, b, c) __builtin_amdgcn_mfma_f32_32x32x16_bf16((a), (b), (c), 0, 0, 0)
; DEV unsigned pk2(float lo, float hi) { return (unsigned)f2bf(lo) | ((unsigned)f2bf(hi) << 16); }
; DEV void attn_compute(const AttnU& a, const bf16x8 (&qf)[4], int tq, bf16_t* OG, float* LSE, LAS unsigned char* lds, int tid) {
;     ...
;     for (int sb = 0; sb < 5; ++sb)
; #pragma unroll
;         for (int rg = 0; rg < 16; ++rg) { const float p = EXP2(s[sb][rg] - mx); s[sb][rg] = p; rs += p; }
;     rs += SHFL_XOR3(rs, 32, lane);
;     f32x16 oacc[2];
; #pragma unroll
;     for (int eb = 0; eb < 2; ++eb)
; #pragma unroll
;         for (int i = 0; i < 16; ++i) oacc[eb][i] = 0.f;
; #pragma unroll
;     for (int sb = 0; sb < 5; ++sb) {
;         if (!vb[sb]) continue;
; #pragma unroll
;         for (int s2 = 0; s2 < 2; ++s2) {
;             u32x4 w;
;             w.x = pk2(s[sb][8 * s2 + 0], s[sb][8 * s2 + 1]); w.y = pk2(s[sb][8 * s2 + 2], s[sb][8 * s2 + 3]);
;             w.z = pk2(s[sb][8 * s2 + 4], s[sb][8 * s2 + 5]); w.w = pk2(s[sb][8 * s2 + 6], s[sb][8 * s2 + 7]);
;             const bf16x8 pf = BITCAST(bf16x8, w);
; #pragma unroll
;             for (int eb = 0; eb < 2; ++eb) {
;                 const LAS unsigned char* vp = lds + AT_V_OFF + (32 * eb + n) * AT_VP + (32 * (wave + sb) + 16 * s2 + 4 * hl) * 2;
;                 const u32x2 lo = *(const LAS u32x2*)vp, hi = *(const LAS u32x2*)(vp + 16);
;                 u32x4 wv; wv.x = lo.x; wv.y = lo.y; wv.z = hi.x; wv.w = hi.y;
;                 oacc[eb] = MFMA32(BITCAST(bf16x8, wv), pf, oacc[eb]);
;             }
	v_sub_f32_e32 v13, v160, v3
	v_add_f32_e32 v12, v182, v12
	v_exp_f32_e32 v171, v13
	v_sub_f32_e32 v13, v163, v3
	v_add_f32_e32 v12, v167, v12
	v_exp_f32_e32 v170, v13
	v_sub_f32_e32 v13, v162, v3
	v_add_f32_e32 v12, v169, v12
	v_exp_f32_e32 v173, v13
	v_sub_f32_e32 v13, v165, v3
	v_add_f32_e32 v12, v168, v12
	v_exp_f32_e32 v172, v13
	v_sub_f32_e32 v13, v164, v3
	v_add_f32_e32 v12, v171, v12
	v_exp_f32_e32 v174, v13
	v_sub_f32_e32 v13, v187, v3
	v_add_f32_e32 v12, v170, v12
	v_exp_f32_e32 v159, v13
	v_sub_f32_e32 v13, v166, v3
	v_add_f32_e32 v12, v173, v12
	v_exp_f32_e32 v161, v13
	v_sub_f32_e32 v13, v193, v3
	v_add_f32_e32 v12, v172, v12
	v_exp_f32_e32 v160, v13
	v_sub_f32_e32 v13, v192, v3
	v_add_f32_e32 v12, v174, v12
	v_exp_f32_e32 v163, v13
	v_sub_f32_e32 v13, v196, v3
	v_add_f32_e32 v12, v159, v12
	v_exp_f32_e32 v162, v13
	v_sub_f32_e32 v13, v195, v3
	v_add_f32_e32 v12, v161, v12
	v_exp_f32_e32 v165, v13
	v_sub_f32_e32 v13, v204, v3
	v_add_f32_e32 v12, v160, v12
	v_exp_f32_e32 v164, v13
	v_sub_f32_e32 v13, v201, v3
	v_add_f32_e32 v12, v163, v12
	v_exp_f32_e32 v166, v13
	v_add_f32_e32 v12, v162, v12
	v_add_f32_e32 v12, v165, v12
	v_add_f32_e32 v12, v164, v12
	v_add_f32_e32 v15, v166, v12
	v_sub_f32_e32 v12, v54, v3
	v_exp_f32_e32 v12, v12
	v_sub_f32_e32 v13, v46, v3
	v_exp_f32_e32 v14, v13
	v_sub_f32_e32 v1, v1, v3
	v_exp_f32_e32 v13, v1
	v_sub_f32_e32 v0, v0, v3
	v_exp_f32_e32 v153, v0
	v_sub_f32_e32 v1, v56, v3
	v_add_f32_e32 v0, v12, v15
	v_exp_f32_e32 v15, v1
	v_sub_f32_e32 v1, v55, v3
	v_add_f32_e32 v0, v14, v0
	v_exp_f32_e32 v155, v1
	v_sub_f32_e32 v1, v5, v3
	v_add_f32_e32 v0, v13, v0
	v_exp_f32_e32 v154, v1
	v_sub_f32_e32 v1, v4, v3
	v_add_f32_e32 v0, v153, v0
	v_exp_f32_e32 v156, v1
	v_sub_f32_e32 v1, v7, v3
	v_add_f32_e32 v0, v15, v0
	v_exp_f32_e32 v4, v1
	v_sub_f32_e32 v1, v6, v3
	v_add_f32_e32 v0, v155, v0
	v_exp_f32_e32 v6, v1
	v_sub_f32_e32 v1, v9, v3
	v_add_f32_e32 v0, v154, v0
	v_exp_f32_e32 v5, v1
	v_sub_f32_e32 v1, v8, v3
	v_add_f32_e32 v0, v156, v0
	v_exp_f32_e32 v8, v1
	v_sub_f32_e32 v1, v11, v3
	v_add_f32_e32 v0, v4, v0
	v_exp_f32_e32 v7, v1
	v_sub_f32_e32 v1, v10, v3
	v_add_f32_e32 v0, v6, v0
	v_exp_f32_e32 v10, v1
	v_sub_f32_e32 v1, v58, v3
	v_add_f32_e32 v0, v5, v0
	v_exp_f32_e32 v9, v1
	v_sub_f32_e32 v1, v57, v3
	v_add_f32_e32 v0, v8, v0
	v_exp_f32_e32 v11, v1
	v_add_f32_e32 v0, v7, v0
	v_add_f32_e32 v0, v10, v0
	v_add_f32_e32 v0, v9, v0
	v_add_f32_e32 v0, v11, v0
	ds_bpermute_b32 v1, v53, v0
	v_lshl_add_u32 v157, v47, 3, 0
	v_mul_u32_u24_e32 v158, 0x308, v147
	v_mov_b32_e32 v79, 0
	v_mov_b32_e32 v80, 0
	v_mov_b32_e32 v81, 0
	v_mov_b32_e32 v82, 0
	v_mov_b32_e32 v83, 0
	v_mov_b32_e32 v84, 0
	v_mov_b32_e32 v85, 0
	v_mov_b32_e32 v86, 0
	v_mov_b32_e32 v87, 0
	v_mov_b32_e32 v88, 0
	v_mov_b32_e32 v89, 0
	v_mov_b32_e32 v90, 0
	v_mov_b32_e32 v91, 0
	v_mov_b32_e32 v92, 0
	v_mov_b32_e32 v93, 0
	v_mov_b32_e32 v94, 0
	v_mov_b32_e32 v95, 0
	v_mov_b32_e32 v96, 0
	v_mov_b32_e32 v97, 0
	v_mov_b32_e32 v98, 0
	v_mov_b32_e32 v99, 0
	v_mov_b32_e32 v100, 0
	v_mov_b32_e32 v101, 0
	v_mov_b32_e32 v102, 0
	v_mov_b32_e32 v103, 0
	v_mov_b32_e32 v104, 0
	v_mov_b32_e32 v105, 0
	v_mov_b32_e32 v106, 0
	v_mov_b32_e32 v107, 0
	v_mov_b32_e32 v108, 0
	v_mov_b32_e32 v109, 0
	v_mov_b32_e32 v46, 0
	v_mov_b32_e32 v47, 0
	v_mov_b32_e32 v48, 0
	v_mov_b32_e32 v49, 0
	v_mov_b32_e32 v50, 0
	v_mov_b32_e32 v51, 0
	v_mov_b32_e32 v52, 0
	v_mov_b32_e32 v53, 0
	v_mov_b32_e32 v54, 0
	v_mov_b32_e32 v55, 0
	v_mov_b32_e32 v56, 0
	v_mov_b32_e32 v57, 0
	v_mov_b32_e32 v58, 0
	v_mov_b32_e32 v62, 0
	v_mov_b32_e32 v63, 0
	v_mov_b32_e32 v64, 0
	v_mov_b32_e32 v65, 0
	v_mov_b32_e32 v66, 0
	v_mov_b32_e32 v67, 0
	v_mov_b32_e32 v68, 0
	v_mov_b32_e32 v69, 0
	v_mov_b32_e32 v70, 0
	v_mov_b32_e32 v71, 0
	v_mov_b32_e32 v72, 0
	v_mov_b32_e32 v73, 0
	v_mov_b32_e32 v74, 0
	v_mov_b32_e32 v75, 0
	v_mov_b32_e32 v76, 0
	v_mov_b32_e32 v77, 0
	s_and_saveexec_b64 s[42:43], s[2:3]
	s_cbranch_execz .LBB0_829
	v_and_b32_e32 v46, 0xffffffc0, v146
	v_add3_u32 v58, v157, v46, v158
	v_add_u32_e32 v59, 0xd800, v58
	ds_read2_b64 v[46:49], v59 offset1:2
	s_mov_b32 s2, 0xffff0000
	v_cvt_pk_bf16_f32 v53, v228, v230
	v_cvt_pk_bf16_f32 v52, v226, v229
	v_cvt_pk_bf16_f32 v51, v224, v227
	v_cvt_pk_bf16_f32 v50, v223, v225
	s_waitcnt lgkmcnt(0)
	s_nop 0
	v_mfma_f32_32x32x16_bf16 v[78:93], v[46:49], v[50:53], 0
	v_add_u32_e32 v46, 0x6100, v58
	v_add_u32_e32 v58, 0xd800, v46
	ds_read2_b64 v[46:49], v58 offset1:2
	ds_read2_b64 v[54:57], v59 offset0:4 offset1:6
	s_waitcnt lgkmcnt(1)
	v_mfma_f32_32x32x16_bf16 v[94:109], v[46:49], v[50:53], 0
	v_bfe_u32 v48, v219, 16, 1
	v_bfe_u32 v49, v217, 16, 1
	v_add3_u32 v50, v217, v49, s17
	v_add3_u32 v51, v219, v48, s17
	v_bfe_u32 v48, v215, 16, 1
	v_bfe_u32 v49, v216, 16, 1
	v_add3_u32 v49, v216, v49, s17
	v_add3_u32 v48, v215, v48, s17
	v_lshrrev_b32_e32 v59, 16, v48
	v_lshrrev_b32_e32 v60, 16, v49
	v_cvt_pk_bf16_f32 v49, v220, v222
	v_cvt_pk_bf16_f32 v48, v218, v221
	v_and_or_b32 v47, v51, s2, v60
	v_and_or_b32 v46, v50, s2, v59
	ds_read2_b64 v[50:53], v58 offset0:4 offset1:6
	s_waitcnt lgkmcnt(1)
	v_mfma_f32_32x32x16_bf16 v[78:93], v[54:57], v[46:49], v[78:93]
	s_waitcnt lgkmcnt(0)
	v_mfma_f32_32x32x16_bf16 v[94:109], v[50:53], v[46:49], v[94:109]
	s_nop 9
	v_mov_b32_e32 v46, v78
	v_mov_b32_e32 v47, v79
	v_mov_b32_e32 v48, v80
	v_mov_b32_e32 v49, v81
	v_mov_b32_e32 v50, v82
	v_mov_b32_e32 v51, v83
	v_mov_b32_e32 v52, v84
	v_mov_b32_e32 v53, v85
	v_mov_b32_e32 v54, v86
	v_mov_b32_e32 v55, v87
	v_mov_b32_e32 v56, v88
	v_mov_b32_e32 v57, v89
	v_mov_b32_e32 v58, v90
	v_mov_b32_e32 v59, v91
	v_mov_b32_e32 v60, v92
	v_mov_b32_e32 v61, v93
	v_mov_b32_e32 v62, v94
	v_mov_b32_e32 v63, v95
	v_mov_b32_e32 v64, v96
	v_mov_b32_e32 v65, v97
	v_mov_b32_e32 v66, v98
	v_mov_b32_e32 v67, v99
	v_mov_b32_e32 v68, v100
	v_mov_b32_e32 v69, v101
	v_mov_b32_e32 v70, v102
	v_mov_b32_e32 v71, v103
	v_mov_b32_e32 v72, v104
	v_mov_b32_e32 v73, v105
	v_mov_b32_e32 v74, v106
	v_mov_b32_e32 v75, v107
	v_mov_b32_e32 v76, v108
	v_mov_b32_e32 v77, v109
	s_or_b64 exec, exec, s[42:43]
	s_and_saveexec_b64 s[2:3], s[6:7]
	s_cbranch_execnz .LBB0_830

; #define LAS __attribute__((address_space(3)))
; #define MFMA32(a, b, c) __builtin_amdgcn_mfma_f32_32x32x16_bf16((a), (b), (c), 0, 0, 0)
; DEV unsigned pk2(float lo, float hi) { return (unsigned)f2bf(lo) | ((unsigned)f2bf(hi) << 16); }
; DEV void attn_compute(const AttnU& a, const bf16x8 (&qf)[4], int tq, bf16_t* OG, float* LSE, LAS unsigned char* lds, int tid) {
;     ...
;     for (int sb = 0; sb < 5; ++sb) {
;         if (!vb[sb]) continue;
; #pragma unroll
;         for (int s2 = 0; s2 < 2; ++s2) {
;             u32x4 w;
;             w.x = pk2(s[sb][8 * s2 + 0], s[sb][8 * s2 + 1]); w.y = pk2(s[sb][8 * s2 + 2], s[sb][8 * s2 + 3]);
;             w.z = pk2(s[sb][8 * s2 + 4], s[sb][8 * s2 + 5]); w.w = pk2(s[sb][8 * s2 + 6], s[sb][8 * s2 + 7]);
;             const bf16x8 pf = BITCAST(bf16x8, w);
; #pragma unroll
;             for (int eb = 0; eb < 2; ++eb) {
;                 const LAS unsigned char* vp = lds + AT_V_OFF + (32 * eb + n) * AT_VP + (32 * (wave + sb) + 16 * s2 + 4 * hl) * 2;
;                 const u32x2 lo = *(const LAS u32x2*)vp, hi = *(const LAS u32x2*)(vp + 16);
;                 u32x4 wv; wv.x = lo.x; wv.y = lo.y; wv.z = hi.x; wv.w = hi.y;
;                 oacc[eb] = MFMA32(BITCAST(bf16x8, wv), pf, oacc[eb]);
;             }
.LBB0_824:
	v_lshlrev_b32_e32 v78, 6, v150
	v_add3_u32 v90, v157, v78, v158
	v_add_u32_e32 v91, 0xd800, v90
	ds_read2_b64 v[78:81], v91 offset1:2
	s_mov_b32 s6, 0xffff0000
	v_cvt_pk_bf16_f32 v85, v189, v191
	v_cvt_pk_bf16_f32 v84, v186, v190
	v_cvt_pk_bf16_f32 v83, v184, v188
	v_cvt_pk_bf16_f32 v82, v183, v185
	s_waitcnt lgkmcnt(0)
	s_nop 0
	v_mfma_f32_32x32x16_bf16 v[46:61], v[78:81], v[82:85], v[46:61]
	v_add_u32_e32 v78, 0x6100, v90
	v_add_u32_e32 v90, 0xd800, v78
	ds_read2_b64 v[78:81], v90 offset1:2
	ds_read2_b64 v[86:89], v91 offset0:4 offset1:6
	s_waitcnt lgkmcnt(1)
	v_mfma_f32_32x32x16_bf16 v[62:77], v[78:81], v[82:85], v[62:77]
	v_bfe_u32 v80, v179, 16, 1
	v_bfe_u32 v81, v177, 16, 1
	v_add3_u32 v82, v177, v81, s17
	v_add3_u32 v83, v179, v80, s17
	v_bfe_u32 v80, v175, 16, 1
	v_bfe_u32 v81, v176, 16, 1
	v_add3_u32 v81, v176, v81, s17
	v_add3_u32 v80, v175, v80, s17
	v_lshrrev_b32_e32 v91, 16, v80
	v_lshrrev_b32_e32 v92, 16, v81
	v_cvt_pk_bf16_f32 v81, v180, v182
	v_cvt_pk_bf16_f32 v80, v178, v181
	v_and_or_b32 v79, v83, s6, v92
	v_and_or_b32 v78, v82, s6, v91
	ds_read2_b64 v[82:85], v90 offset0:4 offset1:6
	s_waitcnt lgkmcnt(1)
	v_mfma_f32_32x32x16_bf16 v[46:61], v[86:89], v[78:81], v[46:61]
	s_waitcnt lgkmcnt(0)
	v_mfma_f32_32x32x16_bf16 v[62:77], v[82:85], v[78:81], v[62:77]
	s_or_b64 exec, exec, s[2:3]
	s_and_saveexec_b64 s[2:3], s[34:35]
	s_cbranch_execnz .LBB0_832

; #define LAS __attribute__((address_space(3)))
; #define MFMA32(a, b, c) __builtin_amdgcn_mfma_f32_32x32x16_bf16((a), (b), (c), 0, 0, 0)
; DEV unsigned pk2(float lo, float hi) { return (unsigned)f2bf(lo) | ((unsigned)f2bf(hi) << 16); }
; DEV void attn_compute(const AttnU& a, const bf16x8 (&qf)[4], int tq, bf16_t* OG, float* LSE, LAS unsigned char* lds, int tid) {
;     ...
;     for (int sb = 0; sb < 5; ++sb) {
;         if (!vb[sb]) continue;
; #pragma unroll
;         for (int s2 = 0; s2 < 2; ++s2) {
;             u32x4 w;
;             w.x = pk2(s[sb][8 * s2 + 0], s[sb][8 * s2 + 1]); w.y = pk2(s[sb][8 * s2 + 2], s[sb][8 * s2 + 3]);
;             w.z = pk2(s[sb][8 * s2 + 4], s[sb][8 * s2 + 5]); w.w = pk2(s[sb][8 * s2 + 6], s[sb][8 * s2 + 7]);
;             const bf16x8 pf = BITCAST(bf16x8, w);
; #pragma unroll
;             for (int eb = 0; eb < 2; ++eb) {
;                 const LAS unsigned char* vp = lds + AT_V_OFF + (32 * eb + n) * AT_VP + (32 * (wave + sb) + 16 * s2 + 4 * hl) * 2;
;                 const u32x2 lo = *(const LAS u32x2*)vp, hi = *(const LAS u32x2*)(vp + 16);
;                 u32x4 wv; wv.x = lo.x; wv.y = lo.y; wv.z = hi.x; wv.w = hi.y;
;                 oacc[eb] = MFMA32(BITCAST(bf16x8, wv), pf, oacc[eb]);
;             }
.LBB0_826:
	v_lshlrev_b32_e32 v78, 6, v152
	v_bfe_u32 v81, v153, 16, 1
	v_bfe_u32 v82, v14, 16, 1
	v_add3_u32 v87, v157, v78, v158
	v_add3_u32 v82, v14, v82, s17
	v_add3_u32 v83, v153, v81, s17
	v_bfe_u32 v14, v12, 16, 1
	v_bfe_u32 v81, v13, 16, 1
	v_bfe_u32 v84, v15, 16, 1
	v_add_u32_e32 v88, 0xd800, v87
	v_add3_u32 v84, v15, v84, s17
	v_add3_u32 v81, v13, v81, s17
	v_add3_u32 v86, v12, v14, s17
	ds_read2_b64 v[12:15], v88 offset1:2
	v_bfe_u32 v80, v155, 16, 1
	v_add3_u32 v80, v155, v80, s17
	v_lshrrev_b32_e32 v78, 16, v86
	v_lshrrev_b32_e32 v86, 16, v81
	v_lshrrev_b32_e32 v84, 16, v84
	s_mov_b32 s6, 0xffff0000
	v_cvt_pk_bf16_f32 v81, v154, v156
	v_and_or_b32 v80, v80, s6, v84
	v_and_or_b32 v79, v83, s6, v86
	v_and_or_b32 v78, v82, s6, v78
	s_waitcnt lgkmcnt(0)
	s_nop 0
	v_mfma_f32_32x32x16_bf16 v[46:61], v[12:15], v[78:81], v[46:61]
	v_add_u32_e32 v12, 0x6100, v87
	v_add_u32_e32 v86, 0xd800, v12
	ds_read2_b64 v[12:15], v86 offset1:2
	ds_read2_b64 v[82:85], v88 offset0:4 offset1:6
	s_waitcnt lgkmcnt(1)
	v_mfma_f32_32x32x16_bf16 v[62:77], v[12:15], v[78:81], v[62:77]
	v_bfe_u32 v12, v11, 16, 1
	v_bfe_u32 v13, v10, 16, 1
	v_bfe_u32 v14, v8, 16, 1
	v_bfe_u32 v15, v6, 16, 1
	v_add3_u32 v15, v6, v15, s17
	v_add3_u32 v8, v8, v14, s17
	v_add3_u32 v6, v10, v13, s17
	v_add3_u32 v10, v11, v12, s17
	v_bfe_u32 v12, v5, 16, 1
	v_bfe_u32 v13, v7, 16, 1
	v_bfe_u32 v14, v9, 16, 1
	v_bfe_u32 v11, v4, 16, 1
	v_add3_u32 v9, v9, v14, s17
	v_add3_u32 v7, v7, v13, s17
	v_add3_u32 v5, v5, v12, s17
	v_add3_u32 v4, v4, v11, s17
	v_lshrrev_b32_e32 v5, 16, v5
	v_lshrrev_b32_e32 v11, 16, v7
	v_lshrrev_b32_e32 v7, 16, v9
	v_and_or_b32 v7, v10, s6, v7
	v_and_or_b32 v6, v6, s6, v11
	v_and_or_b32 v5, v8, s6, v5
	ds_read2_b64 v[8:11], v86 offset0:4 offset1:6
	v_lshrrev_b32_e32 v4, 16, v4
	v_and_or_b32 v4, v15, s6, v4
	s_waitcnt lgkmcnt(1)
	s_nop 0
	v_mfma_f32_32x32x16_bf16 v[46:61], v[82:85], v[4:7], v[46:61]
	s_waitcnt lgkmcnt(0)
	v_mfma_f32_32x32x16_bf16 v[62:77], v[8:11], v[4:7], v[62:77]

; #define LAS __attribute__((address_space(3)))
; #define MFMA32(a, b, c) __builtin_amdgcn_mfma_f32_32x32x16_bf16((a), (b), (c), 0, 0, 0)
; DEV unsigned pk2(float lo, float hi) { return (unsigned)f2bf(lo) | ((unsigned)f2bf(hi) << 16); }
; DEV void attn_compute(const AttnU& a, const bf16x8 (&qf)[4], int tq, bf16_t* OG, float* LSE, LAS unsigned char* lds, int tid) {
;     ...
;     for (int sb = 0; sb < 5; ++sb) {
;         if (!vb[sb]) continue;
; #pragma unroll
;         for (int s2 = 0; s2 < 2; ++s2) {
;             u32x4 w;
;             w.x = pk2(s[sb][8 * s2 + 0], s[sb][8 * s2 + 1]); w.y = pk2(s[sb][8 * s2 + 2], s[sb][8 * s2 + 3]);
;             w.z = pk2(s[sb][8 * s2 + 4], s[sb][8 * s2 + 5]); w.w = pk2(s[sb][8 * s2 + 6], s[sb][8 * s2 + 7]);
;             const bf16x8 pf = BITCAST(bf16x8, w);
; #pragma unroll
;             for (int eb = 0; eb < 2; ++eb) {
;                 const LAS unsigned char* vp = lds + AT_V_OFF + (32 * eb + n) * AT_VP + (32 * (wave + sb) + 16 * s2 + 4 * hl) * 2;
;                 const u32x2 lo = *(const LAS u32x2*)vp, hi = *(const LAS u32x2*)(vp + 16);
;                 u32x4 wv; wv.x = lo.x; wv.y = lo.y; wv.z = hi.x; wv.w = hi.y;
;                 oacc[eb] = MFMA32(BITCAST(bf16x8, wv), pf, oacc[eb]);
;             }
.LBB0_830:
	v_lshlrev_b32_e32 v46, 6, v149
	v_add3_u32 v58, v157, v46, v158
	v_add_u32_e32 v59, 0xd800, v58
	ds_read2_b64 v[46:49], v59 offset1:2
	s_mov_b32 s6, 0xffff0000
	v_cvt_pk_bf16_f32 v53, v212, v214
	v_cvt_pk_bf16_f32 v52, v210, v213
	v_cvt_pk_bf16_f32 v51, v209, v211
	v_cvt_pk_bf16_f32 v50, v208, v207
	s_waitcnt lgkmcnt(0)
	s_nop 0
	v_mfma_f32_32x32x16_bf16 v[78:93], v[46:49], v[50:53], v[78:93]
	v_add_u32_e32 v46, 0x6100, v58
	v_add_u32_e32 v58, 0xd800, v46
	ds_read2_b64 v[46:49], v58 offset1:2
	ds_read2_b64 v[54:57], v59 offset0:4 offset1:6
	s_waitcnt lgkmcnt(1)
	v_mfma_f32_32x32x16_bf16 v[94:109], v[46:49], v[50:53], v[94:109]
	v_bfe_u32 v48, v200, 16, 1
	v_bfe_u32 v49, v198, 16, 1
	v_add3_u32 v50, v198, v49, s17
	v_add3_u32 v51, v200, v48, s17
	v_bfe_u32 v48, v194, 16, 1
	v_bfe_u32 v49, v197, 16, 1
	v_add3_u32 v49, v197, v49, s17
	v_add3_u32 v48, v194, v48, s17
	v_lshrrev_b32_e32 v59, 16, v48
	v_lshrrev_b32_e32 v60, 16, v49
	v_cvt_pk_bf16_f32 v49, v202, v205
	v_cvt_pk_bf16_f32 v48, v199, v203
	v_and_or_b32 v47, v51, s6, v60
	v_and_or_b32 v46, v50, s6, v59
	ds_read2_b64 v[50:53], v58 offset0:4 offset1:6
	s_waitcnt lgkmcnt(1)
	v_mfma_f32_32x32x16_bf16 v[78:93], v[54:57], v[46:49], v[78:93]
	s_waitcnt lgkmcnt(0)
	v_mfma_f32_32x32x16_bf16 v[94:109], v[50:53], v[46:49], v[94:109]
	s_nop 9
	v_mov_b64_e32 v[46:47], v[78:79]
	v_mov_b64_e32 v[48:49], v[80:81]
	v_mov_b64_e32 v[50:51], v[82:83]
	v_mov_b64_e32 v[52:53], v[84:85]
	v_mov_b64_e32 v[54:55], v[86:87]
	v_mov_b64_e32 v[56:57], v[88:89]
	v_mov_b64_e32 v[58:59], v[90:91]
	v_mov_b64_e32 v[60:61], v[92:93]
	v_mov_b64_e32 v[62:63], v[94:95]
	v_mov_b64_e32 v[64:65], v[96:97]
	v_mov_b64_e32 v[66:67], v[98:99]
	v_mov_b64_e32 v[68:69], v[100:101]
	v_mov_b64_e32 v[70:71], v[102:103]
	v_mov_b64_e32 v[72:73], v[104:105]
	v_mov_b64_e32 v[74:75], v[106:107]
	v_mov_b64_e32 v[76:77], v[108:109]
	s_or_b64 exec, exec, s[2:3]
	s_and_saveexec_b64 s[2:3], s[30:31]
	s_cbranch_execnz .LBB0_824

; #define LAS __attribute__((address_space(3)))
; #define MFMA32(a, b, c) __builtin_amdgcn_mfma_f32_32x32x16_bf16((a), (b), (c), 0, 0, 0)
; DEV unsigned pk2(float lo, float hi) { return (unsigned)f2bf(lo) | ((unsigned)f2bf(hi) << 16); }
; DEV void attn_compute(const AttnU& a, const bf16x8 (&qf)[4], int tq, bf16_t* OG, float* LSE, LAS unsigned char* lds, int tid) {
;     ...
;     for (int sb = 0; sb < 5; ++sb) {
;         if (!vb[sb]) continue;
; #pragma unroll
;         for (int s2 = 0; s2 < 2; ++s2) {
;             u32x4 w;
;             w.x = pk2(s[sb][8 * s2 + 0], s[sb][8 * s2 + 1]); w.y = pk2(s[sb][8 * s2 + 2], s[sb][8 * s2 + 3]);
;             w.z = pk2(s[sb][8 * s2 + 4], s[sb][8 * s2 + 5]); w.w = pk2(s[sb][8 * s2 + 6], s[sb][8 * s2 + 7]);
;             const bf16x8 pf = BITCAST(bf16x8, w);
; #pragma unroll
;             for (int eb = 0; eb < 2; ++eb) {
;                 const LAS unsigned char* vp = lds + AT_V_OFF + (32 * eb + n) * AT_VP + (32 * (wave + sb) + 16 * s2 + 4 * hl) * 2;
;                 const u32x2 lo = *(const LAS u32x2*)vp, hi = *(const LAS u32x2*)(vp + 16);
;                 u32x4 wv; wv.x = lo.x; wv.y = lo.y; wv.z = hi.x; wv.w = hi.y;
;                 oacc[eb] = MFMA32(BITCAST(bf16x8, wv), pf, oacc[eb]);
;             }
.LBB0_832:
	v_lshlrev_b32_e32 v78, 6, v151
	v_add3_u32 v90, v157, v78, v158
	v_add_u32_e32 v91, 0xd800, v90
	ds_read2_b64 v[78:81], v91 offset1:2
	s_mov_b32 s6, 0xffff0000
	v_cvt_pk_bf16_f32 v85, v172, v174
	v_cvt_pk_bf16_f32 v84, v170, v173
	v_cvt_pk_bf16_f32 v83, v168, v171
	v_cvt_pk_bf16_f32 v82, v167, v169
	s_waitcnt lgkmcnt(0)
	s_nop 0
	v_mfma_f32_32x32x16_bf16 v[46:61], v[78:81], v[82:85], v[46:61]
	v_add_u32_e32 v78, 0x6100, v90
	v_add_u32_e32 v90, 0xd800, v78
	ds_read2_b64 v[78:81], v90 offset1:2
	ds_read2_b64 v[86:89], v91 offset0:4 offset1:6
	s_waitcnt lgkmcnt(1)
	v_mfma_f32_32x32x16_bf16 v[62:77], v[78:81], v[82:85], v[62:77]
	v_bfe_u32 v80, v163, 16, 1
	v_bfe_u32 v81, v161, 16, 1
	v_add3_u32 v82, v161, v81, s17
	v_add3_u32 v83, v163, v80, s17
	v_bfe_u32 v80, v159, 16, 1
	v_bfe_u32 v81, v160, 16, 1
	v_add3_u32 v81, v160, v81, s17
	v_add3_u32 v80, v159, v80, s17
	v_lshrrev_b32_e32 v91, 16, v80
	v_lshrrev_b32_e32 v92, 16, v81
	v_cvt_pk_bf16_f32 v81, v164, v166
	v_cvt_pk_bf16_f32 v80, v162, v165
	v_and_or_b32 v79, v83, s6, v92
	v_and_or_b32 v78, v82, s6, v91
	ds_read2_b64 v[82:85], v90 offset0:4 offset1:6
	s_waitcnt lgkmcnt(1)
	v_mfma_f32_32x32x16_bf16 v[46:61], v[86:89], v[78:81], v[46:61]
	s_waitcnt lgkmcnt(0)
	v_mfma_f32_32x32x16_bf16 v[62:77], v[82:85], v[78:81], v[62:77]
	s_or_b64 exec, exec, s[2:3]
	s_and_saveexec_b64 s[2:3], s[36:37]
	s_cbranch_execnz .LBB0_826
	s_branch .LBB0_827
